# S5 bf16 LDS image pitch 272 -> 288 B: every ds_read_b128 lane group conflict-free (LDS bank-conflict lever)
# baseline (speedup 1.0000x reference)
; __device__ __forceinline__ unsigned cvtpk(float lo, float hi) { f32x2_t v = {lo, hi}; bf16x2_t b = __builtin_convertvector(v, bf16x2_t); return __builtin_bit_cast(unsigned, b); }
; __device__ __forceinline__ void s5_task(const Args& a, const bf16_t* XN, const float* SS, bf16_t* Y, LAS float* S, int b, int g, int lane) {
;     ...
;     for (int ct = 0; ct < 8; ++ct) { unsigned w[4];
; #pragma unroll
;         for (int jj = 0; jj < 4; ++jj) { float v[2];
; #pragma unroll
;             for (int e = 0; e < 2; ++e) { const float x = BT[((size_t)g * 16 + 8 * (j4 & 1) + 2 * jj + e) * 128 + 8 * n16 + ct]; const float hi = __uint_as_float(cvtpk(x, 0.f) << 16); v[e] = (j4 < 2) ? x : (x - hi); }
;             w[jj] = cvtpk(v[0], v[1]); }
;         bw[ct] = __builtin_bit_cast(bf16x8, (u32x4){w[0], w[1], w[2], w[3]}); }
.LBB0_665:
	s_or_b64 exec, exec, s[28:29]
	s_waitcnt vmcnt(0)
	v_cvt_pk_bf16_f32 v0, v9, 0
	v_lshlrev_b32_e32 v0, 16, v0
	v_sub_f32_e32 v0, v9, v0
	v_cndmask_b32_e32 v147, v0, v9, vcc
	v_cvt_pk_bf16_f32 v0, v2, 0
	v_cvt_pk_bf16_f32 v1, v8, 0
	v_lshlrev_b32_e32 v0, 16, v0
	v_lshlrev_b32_e32 v1, 16, v1
	v_sub_f32_e32 v0, v2, v0
	v_sub_f32_e32 v1, v8, v1
	v_cndmask_b32_e32 v0, v0, v2, vcc
	v_cndmask_b32_e32 v1, v1, v8, vcc
	v_cvt_pk_bf16_f32 v2, v0, v1
	v_cvt_pk_bf16_f32 v0, v6, 0
	v_cvt_pk_bf16_f32 v1, v7, 0
	v_lshlrev_b32_e32 v0, 16, v0
	v_lshlrev_b32_e32 v1, 16, v1
	v_sub_f32_e32 v0, v6, v0
	v_sub_f32_e32 v1, v7, v1
	v_cndmask_b32_e32 v0, v0, v6, vcc
	v_cndmask_b32_e32 v1, v1, v7, vcc
	v_cvt_pk_bf16_f32 v1, v0, v1
	v_cvt_pk_bf16_f32 v0, v4, 0
	v_lshlrev_b32_e32 v0, 16, v0
	v_sub_f32_e32 v0, v4, v0
	v_cndmask_b32_e32 v0, v0, v4, vcc
	v_cvt_pk_bf16_f32 v4, v5, 0
	v_lshlrev_b32_e32 v4, 16, v4
	v_sub_f32_e32 v4, v5, v4
	v_cndmask_b32_e32 v4, v4, v5, vcc
	v_cvt_pk_bf16_f32 v0, v0, v4
	v_cvt_pk_bf16_f32 v4, v74, 0
	v_cvt_pk_bf16_f32 v5, v78, 0
	v_lshlrev_b32_e32 v4, 16, v4
	v_lshlrev_b32_e32 v5, 16, v5
	v_sub_f32_e32 v4, v74, v4
	v_sub_f32_e32 v5, v78, v5
	v_cndmask_b32_e32 v4, v4, v74, vcc
	v_cndmask_b32_e32 v5, v5, v78, vcc
	v_cvt_pk_bf16_f32 v4, v4, v5
	v_cvt_pk_bf16_f32 v5, v66, 0
	v_cvt_pk_bf16_f32 v6, v70, 0
	v_lshlrev_b32_e32 v5, 16, v5
	v_lshlrev_b32_e32 v6, 16, v6
	v_sub_f32_e32 v5, v66, v5
	v_sub_f32_e32 v6, v70, v6
	v_cndmask_b32_e32 v5, v5, v66, vcc
	v_cndmask_b32_e32 v6, v6, v70, vcc
	v_cvt_pk_bf16_f32 v5, v5, v6
	v_cvt_pk_bf16_f32 v6, v40, 0
	v_cvt_pk_bf16_f32 v7, v44, 0
	v_lshlrev_b32_e32 v6, 16, v6
	v_lshlrev_b32_e32 v7, 16, v7
	v_sub_f32_e32 v6, v40, v6
	v_sub_f32_e32 v7, v44, v7
	v_cndmask_b32_e32 v6, v6, v40, vcc
	v_cndmask_b32_e32 v7, v7, v44, vcc
	v_cvt_pk_bf16_f32 v6, v6, v7
	v_cvt_pk_bf16_f32 v7, v16, 0
	v_cvt_pk_bf16_f32 v8, v20, 0
	v_lshlrev_b32_e32 v7, 16, v7
	v_lshlrev_b32_e32 v8, 16, v8
	v_sub_f32_e32 v7, v16, v7
	v_sub_f32_e32 v8, v20, v8
	v_cndmask_b32_e32 v7, v7, v16, vcc
	v_cndmask_b32_e32 v8, v8, v20, vcc
	v_cvt_pk_bf16_f32 v7, v7, v8
	v_cvt_pk_bf16_f32 v8, v75, 0
	v_cvt_pk_bf16_f32 v9, v79, 0
	v_lshlrev_b32_e32 v8, 16, v8
	v_lshlrev_b32_e32 v9, 16, v9
	v_sub_f32_e32 v8, v75, v8
	v_sub_f32_e32 v9, v79, v9
	v_cndmask_b32_e32 v8, v8, v75, vcc
	v_cndmask_b32_e32 v9, v9, v79, vcc
	v_cvt_pk_bf16_f32 v8, v8, v9
	v_cvt_pk_bf16_f32 v9, v67, 0
	v_cvt_pk_bf16_f32 v10, v71, 0
	v_lshlrev_b32_e32 v9, 16, v9
	v_lshlrev_b32_e32 v10, 16, v10
	v_sub_f32_e32 v9, v67, v9
	v_sub_f32_e32 v10, v71, v10
	v_cndmask_b32_e32 v9, v9, v67, vcc
	v_cndmask_b32_e32 v10, v10, v71, vcc
	v_cvt_pk_bf16_f32 v9, v9, v10
	v_cvt_pk_bf16_f32 v10, v41, 0
	v_cvt_pk_bf16_f32 v11, v45, 0
	v_lshlrev_b32_e32 v10, 16, v10
	v_lshlrev_b32_e32 v11, 16, v11
	v_sub_f32_e32 v10, v41, v10
	v_sub_f32_e32 v11, v45, v11
	v_cndmask_b32_e32 v10, v10, v41, vcc
	v_cndmask_b32_e32 v11, v11, v45, vcc
	v_cvt_pk_bf16_f32 v10, v10, v11
	v_cvt_pk_bf16_f32 v11, v17, 0
	v_cvt_pk_bf16_f32 v12, v21, 0
	v_lshlrev_b32_e32 v11, 16, v11
	v_lshlrev_b32_e32 v12, 16, v12
	v_sub_f32_e32 v11, v17, v11
	v_sub_f32_e32 v12, v21, v12
	v_cndmask_b32_e32 v11, v11, v17, vcc
	v_cndmask_b32_e32 v12, v12, v21, vcc
	v_cvt_pk_bf16_f32 v11, v11, v12
	v_cvt_pk_bf16_f32 v12, v76, 0
	v_cvt_pk_bf16_f32 v13, v80, 0
	v_lshlrev_b32_e32 v12, 16, v12
	v_lshlrev_b32_e32 v13, 16, v13
	v_sub_f32_e32 v12, v76, v12
	v_sub_f32_e32 v13, v80, v13
	v_cndmask_b32_e32 v12, v12, v76, vcc
	v_cndmask_b32_e32 v13, v13, v80, vcc
	v_cvt_pk_bf16_f32 v12, v12, v13
	v_cvt_pk_bf16_f32 v13, v68, 0
	v_cvt_pk_bf16_f32 v14, v72, 0
	v_lshlrev_b32_e32 v13, 16, v13
	v_lshlrev_b32_e32 v14, 16, v14
	v_sub_f32_e32 v13, v68, v13
	v_sub_f32_e32 v14, v72, v14
	v_cndmask_b32_e32 v13, v13, v68, vcc
	v_cndmask_b32_e32 v14, v14, v72, vcc
	v_cvt_pk_bf16_f32 v13, v13, v14
	v_cvt_pk_bf16_f32 v14, v42, 0
	v_cvt_pk_bf16_f32 v15, v46, 0
	v_lshlrev_b32_e32 v14, 16, v14
	v_lshlrev_b32_e32 v15, 16, v15
	v_sub_f32_e32 v14, v42, v14
	v_sub_f32_e32 v15, v46, v15
	v_cndmask_b32_e32 v14, v14, v42, vcc
	v_cndmask_b32_e32 v15, v15, v46, vcc
	v_cvt_pk_bf16_f32 v14, v14, v15
	v_cvt_pk_bf16_f32 v15, v18, 0
	v_cvt_pk_bf16_f32 v16, v22, 0
	v_lshlrev_b32_e32 v15, 16, v15
	v_lshlrev_b32_e32 v16, 16, v16
	v_sub_f32_e32 v15, v18, v15
	v_sub_f32_e32 v16, v22, v16
	v_cndmask_b32_e32 v15, v15, v18, vcc
	v_cndmask_b32_e32 v16, v16, v22, vcc
	v_cvt_pk_bf16_f32 v15, v15, v16
	v_cvt_pk_bf16_f32 v16, v77, 0
	v_cvt_pk_bf16_f32 v17, v81, 0
	v_lshlrev_b32_e32 v16, 16, v16
	v_lshlrev_b32_e32 v17, 16, v17
	v_sub_f32_e32 v16, v77, v16
	v_sub_f32_e32 v17, v81, v17
	v_cndmask_b32_e32 v16, v16, v77, vcc
	v_cndmask_b32_e32 v17, v17, v81, vcc
	v_cvt_pk_bf16_f32 v16, v16, v17
	v_cvt_pk_bf16_f32 v17, v69, 0
	v_cvt_pk_bf16_f32 v18, v73, 0
	v_lshlrev_b32_e32 v17, 16, v17
	v_lshlrev_b32_e32 v18, 16, v18
	v_sub_f32_e32 v17, v69, v17
	v_sub_f32_e32 v18, v73, v18
	v_cndmask_b32_e32 v17, v17, v69, vcc
	v_cndmask_b32_e32 v18, v18, v73, vcc
	v_cvt_pk_bf16_f32 v17, v17, v18
	v_cvt_pk_bf16_f32 v18, v43, 0
	v_cvt_pk_bf16_f32 v20, v47, 0
	v_lshlrev_b32_e32 v18, 16, v18
	v_lshlrev_b32_e32 v20, 16, v20
	v_sub_f32_e32 v18, v43, v18
	v_sub_f32_e32 v20, v47, v20
	v_cndmask_b32_e32 v18, v18, v43, vcc
	v_cndmask_b32_e32 v20, v20, v47, vcc
	v_cvt_pk_bf16_f32 v18, v18, v20
	v_cvt_pk_bf16_f32 v20, v19, 0
	v_lshlrev_b32_e32 v20, 16, v20
	v_sub_f32_e32 v20, v19, v20
	v_cndmask_b32_e32 v19, v20, v19, vcc
	v_cvt_pk_bf16_f32 v20, v23, 0
	v_lshlrev_b32_e32 v20, 16, v20
	v_sub_f32_e32 v20, v23, v20
	v_cndmask_b32_e32 v20, v20, v23, vcc
	v_cvt_pk_bf16_f32 v19, v19, v20
	v_cvt_pk_bf16_f32 v20, v54, 0
	v_cvt_pk_bf16_f32 v21, v58, 0
; __device__ __forceinline__ unsigned cvtpk(float lo, float hi) { f32x2_t v = {lo, hi}; bf16x2_t b = __builtin_convertvector(v, bf16x2_t); return __builtin_bit_cast(unsigned, b); }
; #define LAS __attribute__((address_space(3)))
; __device__ __forceinline__ void s5_task(const Args& a, const bf16_t* XN, const float* SS, bf16_t* Y, LAS float* S, int b, int g, int lane) {
;     ...
;     for (int ct = 0; ct < 8; ++ct) { unsigned w[4];
; #pragma unroll
;         for (int jj = 0; jj < 4; ++jj) { float v[2];
; #pragma unroll
;             for (int e = 0; e < 2; ++e) { const float x = BT[((size_t)g * 16 + 8 * (j4 & 1) + 2 * jj + e) * 128 + 8 * n16 + ct]; const float hi = __uint_as_float(cvtpk(x, 0.f) << 16); v[e] = (j4 < 2) ? x : (x - hi); }
;             w[jj] = cvtpk(v[0], v[1]); }
;         bw[ct] = __builtin_bit_cast(bf16x8, (u32x4){w[0], w[1], w[2], w[3]}); }
; #pragma unroll
;     for (int kk = 0; kk < 4; ++kk) { unsigned w[4];
; #pragma unroll
;         for (int jj = 0; jj < 4; ++jj) w[jj] = cvtpk(CT[((size_t)g * 128 + 32 * kk + 8 * j4 + 2 * jj) * 16 + n16], CT[((size_t)g * 128 + 32 * kk + 8 * j4 + 2 * jj + 1) * 16 + n16]);
;         cw[kk] = __builtin_bit_cast(bf16x8, (u32x4){w[0], w[1], w[2], w[3]}); }
;     bf16x8 dw;
;     { unsigned w[4];
; #pragma unroll
;       for (int jj = 0; jj < 4; ++jj) { float v[2];
; #pragma unroll
;           for (int e = 0; e < 2; ++e) { const int c = 8 * (j4 & 1) + 2 * jj + e; const float x = (c == n16) ? a.in[18][g * 16 + n16] : 0.f; const float hi = __uint_as_float(cvtpk(x, 0.f) << 16); v[e] = (j4 < 2) ? x : (x - hi); }
;           w[jj] = cvtpk(v[0], v[1]); }
;       dw = __builtin_bit_cast(bf16x8, (u32x4){w[0], w[1], w[2], w[3]}); }
;     float sre = 0.f, sim = 0.f;
;     const size_t rowb = (size_t)b * SEQ;
;     LAS unsigned short* YS = (LAS unsigned short*)(S + 16 * 132);
;     u32x4 unext = *(const u32x4*)(XN + (rowb + n16) * DM + 16 * g + 8 * (j4 & 1));
;     float ssn = SS[rowb + n16];
	v_lshlrev_b32_e32 v20, 16, v20
	v_lshlrev_b32_e32 v21, 16, v21
	v_sub_f32_e32 v20, v54, v20
	v_sub_f32_e32 v21, v58, v21
	v_cndmask_b32_e32 v20, v20, v54, vcc
	v_cndmask_b32_e32 v21, v21, v58, vcc
	v_cvt_pk_bf16_f32 v20, v20, v21
	v_cvt_pk_bf16_f32 v21, v36, 0
	v_cvt_pk_bf16_f32 v22, v50, 0
	v_lshlrev_b32_e32 v21, 16, v21
	v_lshlrev_b32_e32 v22, 16, v22
	v_sub_f32_e32 v21, v36, v21
	v_sub_f32_e32 v22, v50, v22
	v_cndmask_b32_e32 v21, v21, v36, vcc
	v_cndmask_b32_e32 v22, v22, v50, vcc
	v_cvt_pk_bf16_f32 v21, v21, v22
	v_cvt_pk_bf16_f32 v22, v28, 0
	v_cvt_pk_bf16_f32 v23, v32, 0
	v_lshlrev_b32_e32 v22, 16, v22
	v_lshlrev_b32_e32 v23, 16, v23
	v_sub_f32_e32 v22, v28, v22
	v_sub_f32_e32 v23, v32, v23
	v_cndmask_b32_e32 v22, v22, v28, vcc
	v_cndmask_b32_e32 v23, v23, v32, vcc
	v_cvt_pk_bf16_f32 v22, v22, v23
	v_cvt_pk_bf16_f32 v23, v24, 0
	v_lshlrev_b32_e32 v23, 16, v23
	v_sub_f32_e32 v23, v24, v23
	v_cndmask_b32_e32 v23, v23, v24, vcc
	v_cvt_pk_bf16_f32 v24, v62, 0
	v_lshlrev_b32_e32 v24, 16, v24
	v_sub_f32_e32 v24, v62, v24
	v_cndmask_b32_e32 v24, v24, v62, vcc
	v_cvt_pk_bf16_f32 v23, v23, v24
	v_cvt_pk_bf16_f32 v24, v55, 0
	v_cvt_pk_bf16_f32 v28, v59, 0
	v_lshlrev_b32_e32 v24, 16, v24
	v_lshlrev_b32_e32 v28, 16, v28
	v_sub_f32_e32 v24, v55, v24
	v_sub_f32_e32 v28, v59, v28
	v_cndmask_b32_e32 v24, v24, v55, vcc
	v_cndmask_b32_e32 v28, v28, v59, vcc
	v_cvt_pk_bf16_f32 v40, v24, v28
	v_cvt_pk_bf16_f32 v24, v37, 0
	v_cvt_pk_bf16_f32 v28, v51, 0
	v_lshlrev_b32_e32 v24, 16, v24
	v_lshlrev_b32_e32 v28, 16, v28
	v_sub_f32_e32 v24, v37, v24
	v_sub_f32_e32 v28, v51, v28
	v_cndmask_b32_e32 v24, v24, v37, vcc
	v_cndmask_b32_e32 v28, v28, v51, vcc
	v_cvt_pk_bf16_f32 v41, v24, v28
	v_cvt_pk_bf16_f32 v24, v29, 0
	v_cvt_pk_bf16_f32 v28, v33, 0
	v_lshlrev_b32_e32 v24, 16, v24
	v_lshlrev_b32_e32 v28, 16, v28
	v_sub_f32_e32 v24, v29, v24
	v_sub_f32_e32 v28, v33, v28
	v_cndmask_b32_e32 v24, v24, v29, vcc
	v_cndmask_b32_e32 v28, v28, v33, vcc
	v_cvt_pk_bf16_f32 v42, v24, v28
	v_cvt_pk_bf16_f32 v24, v25, 0
	v_lshlrev_b32_e32 v24, 16, v24
	v_sub_f32_e32 v24, v25, v24
	v_cndmask_b32_e32 v24, v24, v25, vcc
	v_cvt_pk_bf16_f32 v25, v63, 0
	v_lshlrev_b32_e32 v25, 16, v25
	v_sub_f32_e32 v25, v63, v25
	v_cndmask_b32_e32 v25, v25, v63, vcc
	v_cvt_pk_bf16_f32 v43, v24, v25
	v_cvt_pk_bf16_f32 v24, v56, 0
	v_cvt_pk_bf16_f32 v25, v60, 0
	v_lshlrev_b32_e32 v24, 16, v24
	v_lshlrev_b32_e32 v25, 16, v25
	v_sub_f32_e32 v24, v56, v24
	v_sub_f32_e32 v25, v60, v25
	v_cndmask_b32_e32 v24, v24, v56, vcc
	v_cndmask_b32_e32 v25, v25, v60, vcc
	v_cvt_pk_bf16_f32 v44, v24, v25
	v_cvt_pk_bf16_f32 v24, v38, 0
	v_cvt_pk_bf16_f32 v25, v52, 0
	v_lshlrev_b32_e32 v24, 16, v24
	v_lshlrev_b32_e32 v25, 16, v25
	v_sub_f32_e32 v24, v38, v24
	v_sub_f32_e32 v25, v52, v25
	s_and_b32 s28, s43, 0x7f
	v_cndmask_b32_e32 v24, v24, v38, vcc
	v_cndmask_b32_e32 v25, v25, v52, vcc
	s_lshl_b32 s59, s28, 5
	s_add_i32 s28, s56, s35
	v_cvt_pk_bf16_f32 v45, v24, v25
	v_cvt_pk_bf16_f32 v24, v30, 0
	v_cvt_pk_bf16_f32 v25, v34, 0
	s_ashr_i32 s28, s28, 7
	v_lshlrev_b32_e32 v24, 16, v24
	v_lshlrev_b32_e32 v25, 16, v25
	v_sub_f32_e32 v24, v30, v24
	v_sub_f32_e32 v25, v34, v25
	s_ashr_i32 s29, s28, 31
	v_cndmask_b32_e32 v24, v24, v30, vcc
	v_cndmask_b32_e32 v25, v25, v34, vcc
	s_lshl_b64 s[68:69], s[28:29], 11
	v_cvt_pk_bf16_f32 v46, v24, v25
	v_mov_b32_e32 v25, s69
	v_or_b32_e32 v24, s68, v82
	v_lshlrev_b64 v[28:29], 12, v[24:25]
	v_lshl_add_u64 v[28:29], s[40:41], 0, v[28:29]
	s_lshl_b32 s38, s57, 1
	v_lshl_add_u64 v[28:29], v[28:29], 0, s[38:39]
	v_lshlrev_b32_e32 v88, 1, v86
	v_lshl_add_u64 v[28:29], v[28:29], 0, v[88:89]
	v_lshl_add_u64 v[24:25], v[24:25], 2, s[62:63]
	global_load_dwordx4 v[48:51], v[28:29], off
	global_load_dword v124, v[24:25], off
	v_cvt_pk_bf16_f32 v24, v26, 0
	v_cvt_pk_bf16_f32 v25, v64, 0
	v_lshlrev_b32_e32 v24, 16, v24
	v_lshlrev_b32_e32 v25, 16, v25
	v_sub_f32_e32 v24, v26, v24
	v_sub_f32_e32 v25, v64, v25
	v_cndmask_b32_e32 v24, v24, v26, vcc
	v_cndmask_b32_e32 v25, v25, v64, vcc
	v_cvt_pk_bf16_f32 v47, v24, v25
	v_cvt_pk_bf16_f32 v24, v57, 0
	v_cvt_pk_bf16_f32 v25, v61, 0
	v_lshlrev_b32_e32 v24, 16, v24
	v_lshlrev_b32_e32 v25, 16, v25
	v_sub_f32_e32 v24, v57, v24
	v_sub_f32_e32 v25, v61, v25
	v_cndmask_b32_e32 v24, v24, v57, vcc
	v_cndmask_b32_e32 v25, v25, v61, vcc
	v_cvt_pk_bf16_f32 v52, v24, v25
	v_cvt_pk_bf16_f32 v24, v39, 0
	v_cvt_pk_bf16_f32 v25, v53, 0
	v_lshlrev_b32_e32 v24, 16, v24
	v_lshlrev_b32_e32 v25, 16, v25
	v_sub_f32_e32 v24, v39, v24
	v_sub_f32_e32 v25, v53, v25
	v_cndmask_b32_e32 v24, v24, v39, vcc
	v_cndmask_b32_e32 v25, v25, v53, vcc
	v_cvt_pk_bf16_f32 v53, v24, v25
	v_cvt_pk_bf16_f32 v24, v31, 0
	v_cvt_pk_bf16_f32 v25, v35, 0
	v_lshlrev_b32_e32 v24, 16, v24
	v_lshlrev_b32_e32 v25, 16, v25
	v_sub_f32_e32 v24, v31, v24
	v_sub_f32_e32 v25, v35, v25
	v_cndmask_b32_e32 v24, v24, v31, vcc
	v_cndmask_b32_e32 v25, v25, v35, vcc
	v_cvt_pk_bf16_f32 v54, v24, v25
	v_cvt_pk_bf16_f32 v24, v27, 0
	v_cvt_pk_bf16_f32 v25, v65, 0
	v_cvt_pk_bf16_f32 v36, v3, v105
	v_cvt_pk_bf16_f32 v3, v146, 0
	v_lshlrev_b32_e32 v24, 16, v24
	v_lshlrev_b32_e32 v25, 16, v25
	v_lshlrev_b32_e32 v3, 16, v3
	v_sub_f32_e32 v24, v27, v24
	v_sub_f32_e32 v25, v65, v25
	v_sub_f32_e32 v3, v146, v3
	s_lshl_b64 s[60:61], s[28:29], 13
	s_lshl_b64 s[28:29], s[28:29], 23
	v_cndmask_b32_e32 v24, v24, v27, vcc
	v_cndmask_b32_e32 v25, v25, v65, vcc
	v_cndmask_b32_e32 v3, v3, v146, vcc
	s_or_b32 s28, s28, s59
	v_cvt_pk_bf16_f32 v55, v24, v25
	v_cvt_pk_bf16_f32 v37, v106, v107
	v_cvt_pk_bf16_f32 v38, v108, v109
	v_cvt_pk_bf16_f32 v39, v110, v111
	v_cvt_pk_bf16_f32 v32, v112, v114
	v_cvt_pk_bf16_f32 v33, v123, v125
	v_cvt_pk_bf16_f32 v34, v126, v127
	v_cvt_pk_bf16_f32 v35, v128, v129
	v_cvt_pk_bf16_f32 v28, v130, v131
	v_cvt_pk_bf16_f32 v29, v132, v133
	v_cvt_pk_bf16_f32 v30, v134, v135
	v_cvt_pk_bf16_f32 v31, v136, v137
	v_cvt_pk_bf16_f32 v24, v138, v139
	v_cvt_pk_bf16_f32 v25, v140, v141
	v_cvt_pk_bf16_f32 v26, v142, v143
	v_cvt_pk_bf16_f32 v27, v144, v145
	v_cvt_pk_bf16_f32 v3, v147, v3
	v_mov_b32_e32 v76, v102
	v_mov_b32_e32 v77, v102
	v_mov_b32_e32 v78, v103
	v_mov_b32_e32 v79, v103
	v_pk_mov_b32 v[80:81], v[102:103], v[102:103] op_sel:[1,0]
	v_lshl_add_u64 v[106:107], v[96:97], 0, s[60:61]
	v_lshl_add_u64 v[108:109], v[98:99], 0, s[28:29]
	v_lshl_add_u64 v[110:111], v[100:101], 0, s[28:29]
	s_mov_b64 s[28:29], 0
	v_mov_b32_e32 v105, v104
	v_lshl_add_u32 v208, v206, 2, s48
	v_add_u32_e32 v208, 0x12000, v208
	v_and_b32_e32 v209, 15, v206
	v_lshrrev_b32_e32 v210, 4, v206
	v_mul_u32_u24_e32 v209, 0x120, v209
	v_lshl_add_u32 v209, v210, 4, v209
	v_add_u32_e32 v207, s48, v209
	v_add_u32_e32 v207, 0x12000, v207
	s_waitcnt vmcnt(0)
; __device__ __forceinline__ float rs_of(float ss) { return __builtin_amdgcn_rsqf(ss * (1.0f / 2048.0f) + 1e-6f); }
; #define LAS __attribute__((address_space(3)))
; #define LDS_WAIT() asm volatile("s_waitcnt lgkmcnt(0)" ::: "memory")
; #define MFMA16(a, b, c) __builtin_amdgcn_mfma_f32_16x16x32_bf16((a), (b), (c), 0, 0, 0)
; __device__ __forceinline__ void s5_task(const Args& a, const bf16_t* XN, const float* SS, bf16_t* Y, LAS float* S, int b, int g, int lane) {
;     ...
;         const size_t row0 = rowb + blk * 16;
;         const u32x4 uraw = unext; const float rsl = rs_of(ssn);
;         { const size_t rn = (blk + 1 < SEQ / 16) ? row0 + 16 : row0;
;           unext = *(const u32x4*)(XN + (rn + n16) * DM + 16 * g + 8 * (j4 & 1)); ssn = SS[rn + n16]; }
;         float rsw[4];
; #pragma unroll
;         for (int i = 0; i < 4; ++i) rsw[i] = __shfl(rsl, 4 * j4 + i);
;         const bf16x8 ua = __builtin_bit_cast(bf16x8, uraw);
;         f32x4 bu[8];
; #pragma unroll
;         for (int ct = 0; ct < 8; ++ct) bu[ct] = MFMA16(ua, bw[ct], ((f32x4){0.f, 0.f, 0.f, 0.f}));
;         const f32x4 yd = MFMA16(ua, dw, ((f32x4){0.f, 0.f, 0.f, 0.f}));
; #pragma unroll
;         for (int i = 0; i < 4; ++i) { LAS float* w = S + (4 * j4 + i) * 132 + 8 * n16; const float q = rsw[i];
;             *(LAS f32x4*)w = (f32x4){bu[0][i] * q, bu[1][i] * q, bu[2][i] * q, bu[3][i] * q}; *(LAS f32x4*)(w + 4) = (f32x4){bu[4][i] * q, bu[5][i] * q, bu[6][i] * q, bu[7][i] * q}; }
;         LDS_WAIT();
; #pragma unroll
;         for (int tt = 0; tt < 16; ++tt) { LAS f32x2* sp = (LAS f32x2*)(S + tt * 132 + 2 * lane); const f32x2 v = *sp;
;             const float nre = ar * sre - ai * sim + v.x, nim = ar * sim + ai * sre + v.y; sre = nre; sim = nim; *sp = (f32x2){sre, sim}; }
.LBB0_666:
	s_waitcnt vmcnt(1)
	v_mov_b64_e32 v[74:75], v[50:51]
	v_mov_b64_e32 v[72:73], v[48:49]
	s_waitcnt vmcnt(1)
	v_fmamk_f32 v50, v124, 0x3a000000, v119
	v_rsq_f32_e32 v88, v50
	v_pk_mul_f32 v[126:127], v[80:81], v[104:105] op_sel:[0,1]
	v_lshl_add_u64 v[48:49], v[108:109], 0, s[28:29]
	v_mfma_f32_16x16x32_bf16 v[64:67], v[72:75], v[4:7], 0
	ds_bpermute_b32 v154, v113, v88
	ds_bpermute_b32 v114, v115, v88
	ds_bpermute_b32 v112, v116, v88
	v_mfma_f32_16x16x32_bf16 v[56:59], v[72:75], v[8:11], 0
	ds_bpermute_b32 v88, v117, v88
	v_pk_fma_f32 v[152:153], v[102:103], v[104:105], v[126:127] neg_lo:[0,0,1] neg_hi:[0,0,1]
	v_pk_fma_f32 v[104:105], v[102:103], v[104:105], v[126:127] op_sel_hi:[1,0,1]
	v_mfma_f32_16x16x32_bf16 v[68:71], v[72:75], v[12:15], 0
	v_mov_b32_e32 v153, v105
	v_mov_b32_e32 v104, v64
	s_nop 1
	v_mov_b32_e32 v105, v56
	v_mfma_f32_16x16x32_bf16 v[60:63], v[72:75], v[16:19], 0
	v_mov_b32_e32 v56, v65
	s_nop 0
	v_mov_b32_e32 v144, v68
	v_mov_b32_e32 v150, v66
	v_mfma_f32_16x16x32_bf16 v[128:131], v[72:75], v[20:23], 0
	v_mov_b32_e32 v151, v58
	s_nop 1
	v_mov_b32_e32 v145, v60
	v_mov_b32_e32 v60, v69
	v_mfma_f32_16x16x32_bf16 v[132:135], v[72:75], v[40:43], 0
	v_mov_b32_e32 v156, v70
	s_nop 0
	v_mov_b32_e32 v146, v128
	v_mov_b32_e32 v157, v62
	v_mfma_f32_16x16x32_bf16 v[136:139], v[72:75], v[44:47], 0
	v_mov_b32_e32 v158, v130
	s_nop 1
	v_mov_b32_e32 v147, v132
	v_mov_b32_e32 v132, v129
	v_mfma_f32_16x16x32_bf16 v[140:143], v[72:75], v[52:55], 0
	v_mov_b32_e32 v159, v134
	s_nop 0
	v_mov_b32_e32 v148, v136
	v_mov_b32_e32 v172, v138
	v_mov_b32_e32 v58, v67
	v_mov_b32_e32 v62, v71
	s_nop 1
	v_mov_b32_e32 v149, v140
	v_mov_b32_e32 v140, v137
	v_mov_b32_e32 v173, v142
	v_mov_b32_e32 v134, v131
	v_mov_b32_e32 v142, v139
	s_waitcnt lgkmcnt(3)
	v_pk_mul_f32 v[64:65], v[104:105], v[154:155] op_sel_hi:[1,0]
	v_pk_mul_f32 v[66:67], v[144:145], v[154:155] op_sel_hi:[1,0]
	global_load_dword v124, v[106:107], off
	v_pk_mul_f32 v[68:69], v[146:147], v[154:155] op_sel_hi:[1,0]
	global_load_dwordx4 v[48:51], v[48:49], off
	v_pk_mul_f32 v[70:71], v[148:149], v[154:155] op_sel_hi:[1,0]
	s_waitcnt lgkmcnt(2)
	v_pk_mul_f32 v[128:129], v[56:57], v[114:115] op_sel_hi:[1,0]
	v_pk_mul_f32 v[130:131], v[60:61], v[114:115] op_sel_hi:[1,0]
	v_pk_mul_f32 v[136:137], v[132:133], v[114:115] op_sel_hi:[1,0]
	v_pk_mul_f32 v[138:139], v[140:141], v[114:115] op_sel_hi:[1,0]
	s_waitcnt lgkmcnt(1)
	v_pk_mul_f32 v[144:145], v[150:151], v[112:113] op_sel_hi:[1,0]
	v_pk_mul_f32 v[146:147], v[156:157], v[112:113] op_sel_hi:[1,0]
	v_pk_mul_f32 v[148:149], v[158:159], v[112:113] op_sel_hi:[1,0]
	v_pk_mul_f32 v[150:151], v[172:173], v[112:113] op_sel_hi:[1,0]
	s_waitcnt lgkmcnt(0)
	v_pk_mul_f32 v[56:57], v[58:59], v[88:89] op_sel_hi:[1,0]
	v_pk_mul_f32 v[58:59], v[62:63], v[88:89] op_sel_hi:[1,0]
	v_pk_mul_f32 v[60:61], v[134:135], v[88:89] op_sel_hi:[1,0]
	v_pk_mul_f32 v[62:63], v[142:143], v[88:89] op_sel_hi:[1,0]
	ds_write_b128 v120, v[64:67]
	ds_write_b128 v120, v[68:71] offset:16
	ds_write_b128 v120, v[128:131] offset:528
	ds_write_b128 v120, v[136:139] offset:544
	ds_write_b128 v120, v[144:147] offset:1056
	ds_write_b128 v120, v[148:151] offset:1072
	ds_write_b128 v120, v[56:59] offset:1584
	ds_write_b128 v120, v[60:63] offset:1600
	v_add_u32_e32 v123, s48, v87
	s_waitcnt lgkmcnt(0)
	v_add_u32_e32 v125, 0x800, v123
	v_add_u32_e32 v126, 0x1000, v123
	v_add_u32_e32 v127, 0x1800, v123
	ds_read2_b64 v[56:59], v123 offset1:66
	ds_read2_b64 v[60:63], v123 offset0:132 offset1:198
	ds_read2_b64 v[64:67], v125 offset0:8 offset1:74
	ds_read2_b64 v[68:71], v125 offset0:140 offset1:206
	ds_read2_b64 v[128:131], v126 offset0:16 offset1:82
	ds_read2_b64 v[132:135], v126 offset0:148 offset1:214
	ds_read2_b64 v[136:139], v127 offset0:24 offset1:90
	ds_read2_b64 v[140:143], v127 offset0:156 offset1:222
	s_waitcnt lgkmcnt(7)
	v_add_f32_e32 v56, v152, v56
	v_mfma_f32_16x16x32_bf16 v[72:75], v[72:75], v[0:3], 0
	v_add_f32_e32 v57, v153, v57
	v_lshl_add_u64 v[106:107], v[106:107], 0, 64
	v_cvt_pk_bf16_f32 v146, v56, v57
	ds_write_b32 v208, v146
	v_fma_f32 v144, -v103, v57, v58
	v_fma_f32 v145, v103, v56, v59
	v_fma_f32 v58, v102, v56, v144
	v_fma_f32 v59, v102, v57, v145
	v_cvt_pk_bf16_f32 v147, v58, v59
	ds_write_b32 v208, v147 offset:288
	s_waitcnt lgkmcnt(8)
	v_fma_f32 v144, -v103, v59, v60
	v_fma_f32 v145, v103, v58, v61
	v_fma_f32 v60, v102, v58, v144
	v_fma_f32 v61, v102, v59, v145
	v_cvt_pk_bf16_f32 v146, v60, v61
	ds_write_b32 v208, v146 offset:576
	v_fma_f32 v144, -v103, v61, v62
	v_fma_f32 v145, v103, v60, v63
	v_fma_f32 v62, v102, v60, v144
	v_fma_f32 v63, v102, v61, v145
	v_cvt_pk_bf16_f32 v147, v62, v63
	ds_write_b32 v208, v147 offset:864
	s_waitcnt lgkmcnt(9)
	v_fma_f32 v144, -v103, v63, v64
	v_fma_f32 v145, v103, v62, v65
	v_fma_f32 v64, v102, v62, v144
	v_fma_f32 v65, v102, v63, v145
	v_cvt_pk_bf16_f32 v146, v64, v65
	ds_write_b32 v208, v146 offset:1152
	v_fma_f32 v144, -v103, v65, v66
	v_fma_f32 v145, v103, v64, v67
	v_fma_f32 v66, v102, v64, v144
	v_fma_f32 v67, v102, v65, v145
	v_cvt_pk_bf16_f32 v147, v66, v67
	ds_write_b32 v208, v147 offset:1440
	s_waitcnt lgkmcnt(10)
	v_fma_f32 v144, -v103, v67, v68
	v_fma_f32 v145, v103, v66, v69
	v_fma_f32 v68, v102, v66, v144
	v_fma_f32 v69, v102, v67, v145
	v_cvt_pk_bf16_f32 v146, v68, v69
	ds_write_b32 v208, v146 offset:1728
	v_fma_f32 v144, -v103, v69, v70
	v_fma_f32 v145, v103, v68, v71
	v_fma_f32 v70, v102, v68, v144
	v_fma_f32 v71, v102, v69, v145
	v_cvt_pk_bf16_f32 v147, v70, v71
	ds_write_b32 v208, v147 offset:2016
	s_waitcnt lgkmcnt(11)
; __device__ __forceinline__ unsigned cvtpk(float lo, float hi) { f32x2_t v = {lo, hi}; bf16x2_t b = __builtin_convertvector(v, bf16x2_t); return __builtin_bit_cast(unsigned, b); }
; __device__ __forceinline__ float sigmoid_f(float x) { return __builtin_amdgcn_rcpf(1.0f + __builtin_amdgcn_exp2f(-1.4426950408889634f * x)); }
; #define LAS __attribute__((address_space(3)))
; #define LDS_WAIT() asm volatile("s_waitcnt lgkmcnt(0)" ::: "memory")
; #define MFMA16(a, b, c) __builtin_amdgcn_mfma_f32_16x16x32_bf16((a), (b), (c), 0, 0, 0)
; __device__ __forceinline__ void s5_task(const Args& a, const bf16_t* XN, const float* SS, bf16_t* Y, LAS float* S, int b, int g, int lane) {
;     ...
;         for (int tt = 0; tt < 16; ++tt) { LAS f32x2* sp = (LAS f32x2*)(S + tt * 132 + 2 * lane); const f32x2 v = *sp;
;             const float nre = ar * sre - ai * sim + v.x, nim = ar * sim + ai * sre + v.y; sre = nre; sim = nim; *sp = (f32x2){sre, sim}; }
;         LDS_WAIT();
;         f32x4 y = {0.f, 0.f, 0.f, 0.f};
; #pragma unroll
;         for (int kk = 0; kk < 4; ++kk) { const f32x4 s0 = *(LAS f32x4*)(S + n16 * 132 + 32 * kk + 8 * j4), s1 = *(LAS f32x4*)(S + n16 * 132 + 32 * kk + 8 * j4 + 4);
;             const bf16x8 sa = __builtin_bit_cast(bf16x8, (u32x4){cvtpk(s0[0], s0[1]), cvtpk(s0[2], s0[3]), cvtpk(s1[0], s1[1]), cvtpk(s1[2], s1[3])});
;             y = MFMA16(sa, cw[kk], y); }
; #pragma unroll
;         for (int i = 0; i < 4; ++i) { const float v = y[i] + yd[i] * rsw[i];
;             const float ge = v * sigmoid_f(1.5957691216057308f * (v + 0.044715f * v * v * v));
;             YS[(4 * j4 + i) * 16 + n16] = (unsigned short)(cvtpk(ge, 0.f) & 0xffffu); }
;         LDS_WAIT();
;         { const u32x2 o = *(LAS u32x2*)(YS + 4 * lane);
;           *(u32x2*)(Y + (row0 + (lane >> 2)) * DM + 16 * g + 4 * (lane & 3)) = o; }
;         LDS_WAIT();
	v_fma_f32 v144, -v103, v71, v128
	v_fma_f32 v145, v103, v70, v129
	v_fma_f32 v128, v102, v70, v144
	v_fma_f32 v129, v102, v71, v145
	v_cvt_pk_bf16_f32 v146, v128, v129
	ds_write_b32 v208, v146 offset:2304
	v_fma_f32 v144, -v103, v129, v130
	v_fma_f32 v145, v103, v128, v131
	v_fma_f32 v130, v102, v128, v144
	v_fma_f32 v131, v102, v129, v145
	v_cvt_pk_bf16_f32 v147, v130, v131
	ds_write_b32 v208, v147 offset:2592
	s_waitcnt lgkmcnt(12)
	v_fma_f32 v144, -v103, v131, v132
	v_fma_f32 v145, v103, v130, v133
	v_fma_f32 v132, v102, v130, v144
	v_fma_f32 v133, v102, v131, v145
	v_cvt_pk_bf16_f32 v146, v132, v133
	ds_write_b32 v208, v146 offset:2880
	v_fma_f32 v144, -v103, v133, v134
	v_fma_f32 v145, v103, v132, v135
	v_fma_f32 v134, v102, v132, v144
	v_fma_f32 v135, v102, v133, v145
	v_cvt_pk_bf16_f32 v147, v134, v135
	ds_write_b32 v208, v147 offset:3168
	s_waitcnt lgkmcnt(13)
	v_fma_f32 v144, -v103, v135, v136
	v_fma_f32 v145, v103, v134, v137
	v_fma_f32 v136, v102, v134, v144
	v_fma_f32 v137, v102, v135, v145
	v_cvt_pk_bf16_f32 v146, v136, v137
	ds_write_b32 v208, v146 offset:3456
	v_fma_f32 v144, -v103, v137, v138
	v_fma_f32 v145, v103, v136, v139
	v_fma_f32 v138, v102, v136, v144
	v_fma_f32 v139, v102, v137, v145
	v_cvt_pk_bf16_f32 v147, v138, v139
	ds_write_b32 v208, v147 offset:3744
	s_waitcnt lgkmcnt(14)
	v_fma_f32 v144, -v103, v139, v140
	v_fma_f32 v145, v103, v138, v141
	v_fma_f32 v140, v102, v138, v144
	v_fma_f32 v141, v102, v139, v145
	v_cvt_pk_bf16_f32 v146, v140, v141
	ds_write_b32 v208, v146 offset:4032
	v_fma_f32 v144, -v103, v141, v142
	v_fma_f32 v145, v103, v140, v143
	v_fma_f32 v104, v102, v140, v144
	v_fma_f32 v105, v102, v141, v145
	v_cvt_pk_bf16_f32 v147, v104, v105
	ds_write_b32 v208, v147 offset:4320
	s_waitcnt lgkmcnt(0)
	ds_read_b128 v[56:59], v207
	ds_read_b128 v[60:63], v207 offset:64
	ds_read_b128 v[64:67], v207 offset:128
	ds_read_b128 v[68:71], v207 offset:192
	s_waitcnt lgkmcnt(3)
	v_mfma_f32_16x16x32_bf16 v[56:59], v[56:59], v[36:39], 0
	s_waitcnt lgkmcnt(2)
	v_mfma_f32_16x16x32_bf16 v[56:59], v[60:63], v[32:35], v[56:59]
	s_waitcnt lgkmcnt(1)
	v_mfma_f32_16x16x32_bf16 v[56:59], v[64:67], v[28:31], v[56:59]
	s_waitcnt lgkmcnt(0)
	v_mfma_f32_16x16x32_bf16 v[56:59], v[68:71], v[24:27], v[56:59]
	s_nop 7
	v_fma_f32 v56, v72, v154, v56
	v_fma_f32 v57, v73, v114, v57
	v_fma_f32 v58, v74, v112, v58
	v_fmac_f32_e32 v59, v75, v88
	v_mul_f32_e32 v60, 0x3d372713, v56
	v_mul_f32_e32 v61, 0x3d372713, v57
	v_mul_f32_e32 v62, 0x3d372713, v58
	v_mul_f32_e32 v63, 0x3d372713, v59
	v_mul_f32_e32 v60, v56, v60
	v_mul_f32_e32 v61, v57, v61
	v_mul_f32_e32 v62, v58, v62
	v_mul_f32_e32 v63, v59, v63
	v_fma_f32 v60, v56, v60, v56
	v_fma_f32 v61, v57, v61, v57
	v_fma_f32 v62, v58, v62, v58
	v_fma_f32 v63, v59, v63, v59
	v_mul_f32_e32 v60, 0x3fcc422a, v60
	v_mul_f32_e32 v61, 0x3fcc422a, v61
	v_mul_f32_e32 v62, 0x3fcc422a, v62
	v_mul_f32_e32 v63, 0x3fcc422a, v63
	v_mul_f32_e32 v60, 0xbfb8aa3b, v60
	v_mul_f32_e32 v61, 0xbfb8aa3b, v61
	v_mul_f32_e32 v62, 0xbfb8aa3b, v62
	v_mul_f32_e32 v63, 0xbfb8aa3b, v63
	v_exp_f32_e32 v60, v60
	v_exp_f32_e32 v61, v61
	v_exp_f32_e32 v62, v62
	v_exp_f32_e32 v63, v63
	v_add_f32_e32 v60, 1.0, v60
	v_add_f32_e32 v61, 1.0, v61
	v_add_f32_e32 v62, 1.0, v62
	v_add_f32_e32 v63, 1.0, v63
	v_rcp_f32_e32 v60, v60
	v_rcp_f32_e32 v61, v61
	v_rcp_f32_e32 v62, v62
	v_rcp_f32_e32 v63, v63
	v_mul_f32_e32 v56, v56, v60
	v_mul_f32_e32 v57, v57, v61
	v_mul_f32_e32 v58, v58, v62
	v_mul_f32_e32 v59, v59, v63
	v_cvt_pk_bf16_f32 v56, v56, s0
	v_cvt_pk_bf16_f32 v57, v57, s0
	v_cvt_pk_bf16_f32 v58, v58, s0
	v_cvt_pk_bf16_f32 v59, v59, s0
	ds_write_b16 v122, v56 offset:8448
	ds_write_b16 v122, v57 offset:8480
	ds_write_b16 v122, v58 offset:8512
	ds_write_b16 v122, v59 offset:8544
	s_waitcnt lgkmcnt(0)
	ds_read_b64 v[56:57], v123 offset:8448
	v_lshl_add_u64 v[58:59], v[110:111], 0, s[28:29]
	s_add_u32 s28, s28, 0x10000
	s_addc_u32 s29, s29, 0
	s_cmp_lg_u32 s28, 0x7f0000
	s_waitcnt lgkmcnt(0)
	global_store_dwordx2 v[58:59], v[56:57], off
	s_waitcnt lgkmcnt(0)
	s_cbranch_scc1 .LBB0_666
	s_waitcnt vmcnt(1)
	v_mfma_f32_16x16x32_bf16 v[56:59], v[48:51], v[4:7], 0
	v_fmamk_f32 v4, v124, 0x3a000000, v119
	v_rsq_f32_e32 v4, v4
	s_lshl_b32 s38, s57, 1
	v_mfma_f32_16x16x32_bf16 v[60:63], v[48:51], v[8:11], 0
	s_add_i32 s56, s56, s50
	ds_bpermute_b32 v10, v113, v4
	ds_bpermute_b32 v8, v115, v4
	v_mfma_f32_16x16x32_bf16 v[12:15], v[48:51], v[12:15], 0
	v_mov_b32_e32 v64, v56
	s_nop 2
	v_mov_b32_e32 v65, v60
	ds_bpermute_b32 v6, v116, v4
	v_mfma_f32_16x16x32_bf16 v[16:19], v[48:51], v[16:19], 0
	s_waitcnt lgkmcnt(2)
	v_pk_mul_f32 v[64:65], v[64:65], v[10:11] op_sel_hi:[1,0]
	v_mov_b32_e32 v66, v12
	v_mov_b32_e32 v60, v57
	v_mfma_f32_16x16x32_bf16 v[20:23], v[48:51], v[20:23], 0
	ds_bpermute_b32 v4, v117, v4
	s_nop 1
	v_mov_b32_e32 v67, v16
	v_pk_mul_f32 v[66:67], v[66:67], v[10:11] op_sel_hi:[1,0]
	v_mfma_f32_16x16x32_bf16 v[40:43], v[48:51], v[40:43], 0
	ds_write_b128 v120, v[64:67]
	s_nop 0
	v_mov_b32_e32 v64, v20
	v_mov_b32_e32 v16, v13
	v_mfma_f32_16x16x32_bf16 v[44:47], v[48:51], v[44:47], 0
	v_mov_b32_e32 v12, v58
	s_nop 1
	v_mov_b32_e32 v65, v40
	v_pk_mul_f32 v[64:65], v[64:65], v[10:11] op_sel_hi:[1,0]
	v_mfma_f32_16x16x32_bf16 v[52:55], v[48:51], v[52:55], 0
	v_mov_b32_e32 v40, v21
	s_nop 0
	v_mov_b32_e32 v66, v44
	v_mov_b32_e32 v13, v62
	v_mov_b32_e32 v62, v59
	v_mfma_f32_16x16x32_bf16 v[0:3], v[48:51], v[0:3], 0
	s_nop 1
	v_mov_b32_e32 v67, v52
	v_pk_mul_f32 v[66:67], v[66:67], v[10:11] op_sel_hi:[1,0]
	ds_write_b128 v120, v[64:67] offset:16
	s_waitcnt lgkmcnt(4)
; #define LAS __attribute__((address_space(3)))
; #define LDS_WAIT() asm volatile("s_waitcnt lgkmcnt(0)" ::: "memory")
; #define MFMA16(a, b, c) __builtin_amdgcn_mfma_f32_16x16x32_bf16((a), (b), (c), 0, 0, 0)
; __device__ __forceinline__ void s5_task(const Args& a, const bf16_t* XN, const float* SS, bf16_t* Y, LAS float* S, int b, int g, int lane) {
;     ...
;         float rsw[4];
; #pragma unroll
;         for (int i = 0; i < 4; ++i) rsw[i] = __shfl(rsl, 4 * j4 + i);
;         const bf16x8 ua = __builtin_bit_cast(bf16x8, uraw);
;         f32x4 bu[8];
; #pragma unroll
;         for (int ct = 0; ct < 8; ++ct) bu[ct] = MFMA16(ua, bw[ct], ((f32x4){0.f, 0.f, 0.f, 0.f}));
;         const f32x4 yd = MFMA16(ua, dw, ((f32x4){0.f, 0.f, 0.f, 0.f}));
; #pragma unroll
;         for (int i = 0; i < 4; ++i) { LAS float* w = S + (4 * j4 + i) * 132 + 8 * n16; const float q = rsw[i];
;             *(LAS f32x4*)w = (f32x4){bu[0][i] * q, bu[1][i] * q, bu[2][i] * q, bu[3][i] * q}; *(LAS f32x4*)(w + 4) = (f32x4){bu[4][i] * q, bu[5][i] * q, bu[6][i] * q, bu[7][i] * q}; }
;         LDS_WAIT();
; #pragma unroll
;         for (int tt = 0; tt < 16; ++tt) { LAS f32x2* sp = (LAS f32x2*)(S + tt * 132 + 2 * lane); const f32x2 v = *sp;
;             const float nre = ar * sre - ai * sim + v.x, nim = ar * sim + ai * sre + v.y; sre = nre; sim = nim; *sp = (f32x2){sre, sim}; }
	v_pk_mul_f32 v[64:65], v[60:61], v[8:9] op_sel_hi:[1,0]
	v_pk_mul_f32 v[66:67], v[16:17], v[8:9] op_sel_hi:[1,0]
	v_mov_b32_e32 v52, v45
	ds_write_b128 v120, v[64:67] offset:528
	v_pk_mul_f32 v[64:65], v[40:41], v[8:9] op_sel_hi:[1,0]
	v_pk_mul_f32 v[66:67], v[52:53], v[8:9] op_sel_hi:[1,0]
	ds_write_b128 v120, v[64:67] offset:544
	s_waitcnt lgkmcnt(5)
	v_pk_mul_f32 v[64:65], v[12:13], v[6:7] op_sel_hi:[1,0]
	v_mov_b32_e32 v12, v14
	v_mov_b32_e32 v13, v18
	v_pk_mul_f32 v[66:67], v[12:13], v[6:7] op_sel_hi:[1,0]
	v_mov_b32_e32 v12, v22
	v_mov_b32_e32 v13, v42
	ds_write_b128 v120, v[64:67] offset:1056
	v_pk_mul_f32 v[64:65], v[12:13], v[6:7] op_sel_hi:[1,0]
	v_mov_b32_e32 v12, v46
	v_mov_b32_e32 v13, v54
	v_mov_b32_e32 v18, v15
	v_pk_mul_f32 v[66:67], v[12:13], v[6:7] op_sel_hi:[1,0]
	s_waitcnt lgkmcnt(5)
	v_pk_mul_f32 v[12:13], v[62:63], v[4:5] op_sel_hi:[1,0]
	v_pk_mul_f32 v[14:15], v[18:19], v[4:5] op_sel_hi:[1,0]
	v_mov_b32_e32 v42, v23
	v_mov_b32_e32 v54, v47
	ds_write_b128 v120, v[12:15] offset:1584
	v_pk_mul_f32 v[12:13], v[42:43], v[4:5] op_sel_hi:[1,0]
	v_pk_mul_f32 v[14:15], v[54:55], v[4:5] op_sel_hi:[1,0]
	ds_write_b128 v120, v[64:67] offset:1072
	ds_write_b128 v120, v[12:15] offset:1600
	s_waitcnt lgkmcnt(0)
	ds_read2_b64 v[12:15], v123 offset1:66
	v_pk_mul_f32 v[16:17], v[80:81], v[104:105] op_sel:[0,1]
	s_add_i32 s43, s43, s49
	v_pk_fma_f32 v[18:19], v[102:103], v[104:105], v[16:17] neg_lo:[0,0,1] neg_hi:[0,0,1]
	v_pk_fma_f32 v[16:17], v[102:103], v[104:105], v[16:17] op_sel_hi:[1,0,1]
	s_cmp_ge_i32 s56, s34
	v_mov_b32_e32 v19, v17
	s_waitcnt lgkmcnt(0)
	v_pk_add_f32 v[12:13], v[18:19], v[12:13]
	s_nop 0
	v_pk_mul_f32 v[16:17], v[78:79], v[12:13]
	s_nop 0
	v_pk_fma_f32 v[18:19], v[76:77], v[12:13], v[16:17] op_sel:[0,0,1] op_sel_hi:[1,1,0] neg_lo:[0,0,1] neg_hi:[0,0,1]
	v_pk_fma_f32 v[16:17], v[76:77], v[12:13], v[16:17] op_sel:[0,0,1] op_sel_hi:[1,1,0]
	s_nop 0
	v_mov_b32_e32 v19, v17
	v_pk_add_f32 v[16:17], v[14:15], v[18:19]
	ds_write2_b64 v123, v[12:13], v[16:17] offset1:66
	ds_read2_b64 v[12:15], v123 offset0:132 offset1:198
	v_pk_mul_f32 v[18:19], v[78:79], v[16:17]
	s_nop 0
	v_pk_fma_f32 v[20:21], v[76:77], v[16:17], v[18:19] op_sel:[0,0,1] op_sel_hi:[1,1,0] neg_lo:[0,0,1] neg_hi:[0,0,1]
	v_pk_fma_f32 v[16:17], v[76:77], v[16:17], v[18:19] op_sel:[0,0,1] op_sel_hi:[1,1,0]
	s_nop 0
	v_mov_b32_e32 v21, v17
	s_waitcnt lgkmcnt(0)
	v_pk_add_f32 v[12:13], v[12:13], v[20:21]
	s_nop 0
	v_pk_mul_f32 v[16:17], v[78:79], v[12:13]
	s_nop 0
	v_pk_fma_f32 v[18:19], v[76:77], v[12:13], v[16:17] op_sel:[0,0,1] op_sel_hi:[1,1,0] neg_lo:[0,0,1] neg_hi:[0,0,1]
	v_pk_fma_f32 v[16:17], v[76:77], v[12:13], v[16:17] op_sel:[0,0,1] op_sel_hi:[1,1,0]
	s_nop 0
	v_mov_b32_e32 v19, v17
	v_pk_add_f32 v[16:17], v[14:15], v[18:19]
	ds_write2_b64 v123, v[12:13], v[16:17] offset0:132 offset1:198
	ds_read2_b64 v[12:15], v125 offset0:8 offset1:74
	v_pk_mul_f32 v[18:19], v[78:79], v[16:17]
	s_nop 0
	v_pk_fma_f32 v[20:21], v[76:77], v[16:17], v[18:19] op_sel:[0,0,1] op_sel_hi:[1,1,0] neg_lo:[0,0,1] neg_hi:[0,0,1]
	v_pk_fma_f32 v[16:17], v[76:77], v[16:17], v[18:19] op_sel:[0,0,1] op_sel_hi:[1,1,0]
	s_nop 0
	v_mov_b32_e32 v21, v17
	s_waitcnt lgkmcnt(0)
	v_pk_add_f32 v[12:13], v[12:13], v[20:21]
	s_nop 0
	v_pk_mul_f32 v[16:17], v[78:79], v[12:13]
	s_nop 0
	v_pk_fma_f32 v[18:19], v[76:77], v[12:13], v[16:17] op_sel:[0,0,1] op_sel_hi:[1,1,0] neg_lo:[0,0,1] neg_hi:[0,0,1]
	v_pk_fma_f32 v[16:17], v[76:77], v[12:13], v[16:17] op_sel:[0,0,1] op_sel_hi:[1,1,0]
	s_nop 0
	v_mov_b32_e32 v19, v17
	v_pk_add_f32 v[16:17], v[14:15], v[18:19]
	ds_write2_b64 v125, v[12:13], v[16:17] offset0:8 offset1:74
	ds_read2_b64 v[12:15], v125 offset0:140 offset1:206
	v_pk_mul_f32 v[18:19], v[78:79], v[16:17]
	s_nop 0
	v_pk_fma_f32 v[20:21], v[76:77], v[16:17], v[18:19] op_sel:[0,0,1] op_sel_hi:[1,1,0] neg_lo:[0,0,1] neg_hi:[0,0,1]
	v_pk_fma_f32 v[16:17], v[76:77], v[16:17], v[18:19] op_sel:[0,0,1] op_sel_hi:[1,1,0]
	s_nop 0
	v_mov_b32_e32 v21, v17
	s_waitcnt lgkmcnt(0)
	v_pk_add_f32 v[12:13], v[12:13], v[20:21]
	s_nop 0
	v_pk_mul_f32 v[16:17], v[78:79], v[12:13]
	s_nop 0
	v_pk_fma_f32 v[18:19], v[76:77], v[12:13], v[16:17] op_sel:[0,0,1] op_sel_hi:[1,1,0] neg_lo:[0,0,1] neg_hi:[0,0,1]
	v_pk_fma_f32 v[16:17], v[76:77], v[12:13], v[16:17] op_sel:[0,0,1] op_sel_hi:[1,1,0]
	s_nop 0
	v_mov_b32_e32 v19, v17
	v_pk_add_f32 v[16:17], v[14:15], v[18:19]
	ds_write2_b64 v125, v[12:13], v[16:17] offset0:140 offset1:206
	ds_read2_b64 v[12:15], v126 offset0:16 offset1:82
	v_pk_mul_f32 v[18:19], v[78:79], v[16:17]
	s_nop 0
	v_pk_fma_f32 v[20:21], v[76:77], v[16:17], v[18:19] op_sel:[0,0,1] op_sel_hi:[1,1,0] neg_lo:[0,0,1] neg_hi:[0,0,1]
	v_pk_fma_f32 v[16:17], v[76:77], v[16:17], v[18:19] op_sel:[0,0,1] op_sel_hi:[1,1,0]
	s_nop 0
	v_mov_b32_e32 v21, v17
	s_waitcnt lgkmcnt(0)
	v_pk_add_f32 v[12:13], v[12:13], v[20:21]
	s_nop 0
	v_pk_mul_f32 v[16:17], v[78:79], v[12:13]
	s_nop 0
	v_pk_fma_f32 v[18:19], v[76:77], v[12:13], v[16:17] op_sel:[0,0,1] op_sel_hi:[1,1,0] neg_lo:[0,0,1] neg_hi:[0,0,1]
	v_pk_fma_f32 v[16:17], v[76:77], v[12:13], v[16:17] op_sel:[0,0,1] op_sel_hi:[1,1,0]
	s_nop 0
	v_mov_b32_e32 v19, v17
	v_pk_add_f32 v[16:17], v[14:15], v[18:19]
	ds_write2_b64 v126, v[12:13], v[16:17] offset0:16 offset1:82
	ds_read2_b64 v[12:15], v126 offset0:148 offset1:214
	v_pk_mul_f32 v[18:19], v[78:79], v[16:17]
	s_nop 0
	v_pk_fma_f32 v[20:21], v[76:77], v[16:17], v[18:19] op_sel:[0,0,1] op_sel_hi:[1,1,0] neg_lo:[0,0,1] neg_hi:[0,0,1]
	v_pk_fma_f32 v[16:17], v[76:77], v[16:17], v[18:19] op_sel:[0,0,1] op_sel_hi:[1,1,0]
	s_nop 0
	v_mov_b32_e32 v21, v17
	s_waitcnt lgkmcnt(0)
; __device__ __forceinline__ unsigned cvtpk(float lo, float hi) { f32x2_t v = {lo, hi}; bf16x2_t b = __builtin_convertvector(v, bf16x2_t); return __builtin_bit_cast(unsigned, b); }
; __device__ __forceinline__ float sigmoid_f(float x) { return __builtin_amdgcn_rcpf(1.0f + __builtin_amdgcn_exp2f(-1.4426950408889634f * x)); }
; #define LAS __attribute__((address_space(3)))
; #define LDS_WAIT() asm volatile("s_waitcnt lgkmcnt(0)" ::: "memory")
; #define MFMA16(a, b, c) __builtin_amdgcn_mfma_f32_16x16x32_bf16((a), (b), (c), 0, 0, 0)
; __device__ __forceinline__ void s5_task(const Args& a, const bf16_t* XN, const float* SS, bf16_t* Y, LAS float* S, int b, int g, int lane) {
;     ...
;         for (int tt = 0; tt < 16; ++tt) { LAS f32x2* sp = (LAS f32x2*)(S + tt * 132 + 2 * lane); const f32x2 v = *sp;
;             const float nre = ar * sre - ai * sim + v.x, nim = ar * sim + ai * sre + v.y; sre = nre; sim = nim; *sp = (f32x2){sre, sim}; }
;         LDS_WAIT();
;         f32x4 y = {0.f, 0.f, 0.f, 0.f};
; #pragma unroll
;         for (int kk = 0; kk < 4; ++kk) { const f32x4 s0 = *(LAS f32x4*)(S + n16 * 132 + 32 * kk + 8 * j4), s1 = *(LAS f32x4*)(S + n16 * 132 + 32 * kk + 8 * j4 + 4);
;             const bf16x8 sa = __builtin_bit_cast(bf16x8, (u32x4){cvtpk(s0[0], s0[1]), cvtpk(s0[2], s0[3]), cvtpk(s1[0], s1[1]), cvtpk(s1[2], s1[3])});
;             y = MFMA16(sa, cw[kk], y); }
; #pragma unroll
;         for (int i = 0; i < 4; ++i) { const float v = y[i] + yd[i] * rsw[i];
;             const float ge = v * sigmoid_f(1.5957691216057308f * (v + 0.044715f * v * v * v));
;             YS[(4 * j4 + i) * 16 + n16] = (unsigned short)(cvtpk(ge, 0.f) & 0xffffu); }
;         LDS_WAIT();
;         { const u32x2 o = *(LAS u32x2*)(YS + 4 * lane);
;           *(u32x2*)(Y + (row0 + (lane >> 2)) * DM + 16 * g + 4 * (lane & 3)) = o; }
;         LDS_WAIT();
	v_pk_add_f32 v[12:13], v[12:13], v[20:21]
	s_nop 0
	v_pk_mul_f32 v[16:17], v[78:79], v[12:13]
	s_nop 0
	v_pk_fma_f32 v[18:19], v[76:77], v[12:13], v[16:17] op_sel:[0,0,1] op_sel_hi:[1,1,0] neg_lo:[0,0,1] neg_hi:[0,0,1]
	v_pk_fma_f32 v[16:17], v[76:77], v[12:13], v[16:17] op_sel:[0,0,1] op_sel_hi:[1,1,0]
	s_nop 0
	v_mov_b32_e32 v19, v17
	v_pk_add_f32 v[16:17], v[14:15], v[18:19]
	ds_write2_b64 v126, v[12:13], v[16:17] offset0:148 offset1:214
	ds_read2_b64 v[12:15], v127 offset0:24 offset1:90
	v_pk_mul_f32 v[18:19], v[78:79], v[16:17]
	s_nop 0
	v_pk_fma_f32 v[20:21], v[76:77], v[16:17], v[18:19] op_sel:[0,0,1] op_sel_hi:[1,1,0] neg_lo:[0,0,1] neg_hi:[0,0,1]
	v_pk_fma_f32 v[16:17], v[76:77], v[16:17], v[18:19] op_sel:[0,0,1] op_sel_hi:[1,1,0]
	s_nop 0
	v_mov_b32_e32 v21, v17
	s_waitcnt lgkmcnt(0)
	v_pk_add_f32 v[12:13], v[12:13], v[20:21]
	s_nop 0
	v_pk_mul_f32 v[16:17], v[78:79], v[12:13]
	s_nop 0
	v_pk_fma_f32 v[18:19], v[76:77], v[12:13], v[16:17] op_sel:[0,0,1] op_sel_hi:[1,1,0] neg_lo:[0,0,1] neg_hi:[0,0,1]
	v_pk_fma_f32 v[16:17], v[76:77], v[12:13], v[16:17] op_sel:[0,0,1] op_sel_hi:[1,1,0]
	s_nop 0
	v_mov_b32_e32 v19, v17
	v_pk_add_f32 v[16:17], v[14:15], v[18:19]
	ds_write2_b64 v127, v[12:13], v[16:17] offset0:24 offset1:90
	ds_read2_b64 v[12:15], v127 offset0:156 offset1:222
	v_pk_mul_f32 v[18:19], v[78:79], v[16:17]
	s_nop 0
	v_pk_fma_f32 v[20:21], v[76:77], v[16:17], v[18:19] op_sel:[0,0,1] op_sel_hi:[1,1,0] neg_lo:[0,0,1] neg_hi:[0,0,1]
	v_pk_fma_f32 v[16:17], v[76:77], v[16:17], v[18:19] op_sel:[0,0,1] op_sel_hi:[1,1,0]
	s_nop 0
	v_mov_b32_e32 v21, v17
	s_waitcnt lgkmcnt(0)
	v_pk_add_f32 v[12:13], v[12:13], v[20:21]
	s_nop 0
	v_pk_mul_f32 v[16:17], v[78:79], v[12:13]
	s_nop 0
	v_pk_fma_f32 v[18:19], v[76:77], v[12:13], v[16:17] op_sel:[0,0,1] op_sel_hi:[1,1,0] neg_lo:[0,0,1] neg_hi:[0,0,1]
	v_pk_fma_f32 v[16:17], v[76:77], v[12:13], v[16:17] op_sel:[0,0,1] op_sel_hi:[1,1,0]
	s_nop 0
	v_mov_b32_e32 v19, v17
	v_pk_add_f32 v[14:15], v[14:15], v[18:19]
	ds_write2_b64 v127, v[12:13], v[14:15] offset0:156 offset1:222
	s_waitcnt lgkmcnt(0)
	ds_read_b128 v[12:15], v121
	ds_read_b128 v[16:19], v121 offset:16
	s_waitcnt lgkmcnt(1)
	v_cvt_pk_bf16_f32 v12, v12, v13
	v_cvt_pk_bf16_f32 v13, v14, v15
	s_waitcnt lgkmcnt(0)
	v_cvt_pk_bf16_f32 v14, v16, v17
	v_cvt_pk_bf16_f32 v15, v18, v19
	ds_read_b128 v[16:19], v121 offset:128
	ds_read_b128 v[20:23], v121 offset:144
	v_mfma_f32_16x16x32_bf16 v[12:15], v[12:15], v[36:39], 0
	s_waitcnt lgkmcnt(1)
	v_cvt_pk_bf16_f32 v16, v16, v17
	v_cvt_pk_bf16_f32 v17, v18, v19
	s_waitcnt lgkmcnt(0)
	v_cvt_pk_bf16_f32 v18, v20, v21
	v_cvt_pk_bf16_f32 v19, v22, v23
	ds_read_b128 v[20:23], v121 offset:256
	ds_read_b128 v[36:39], v121 offset:272
	v_mfma_f32_16x16x32_bf16 v[12:15], v[16:19], v[32:35], v[12:15]
	s_waitcnt lgkmcnt(1)
	v_cvt_pk_bf16_f32 v16, v20, v21
	v_cvt_pk_bf16_f32 v17, v22, v23
	s_waitcnt lgkmcnt(0)
	v_cvt_pk_bf16_f32 v18, v36, v37
	v_cvt_pk_bf16_f32 v19, v38, v39
	ds_read_b128 v[20:23], v121 offset:384
	ds_read_b128 v[32:35], v121 offset:400
	v_mfma_f32_16x16x32_bf16 v[12:15], v[16:19], v[28:31], v[12:15]
	s_waitcnt lgkmcnt(1)
	v_cvt_pk_bf16_f32 v16, v20, v21
	v_cvt_pk_bf16_f32 v17, v22, v23
	s_waitcnt lgkmcnt(0)
	v_cvt_pk_bf16_f32 v18, v32, v33
	v_cvt_pk_bf16_f32 v19, v34, v35
	s_nop 1
	v_mfma_f32_16x16x32_bf16 v[12:15], v[16:19], v[24:27], v[12:15]
	s_nop 7
	v_fma_f32 v0, v0, v10, v12
	v_mul_f32_e32 v5, 0x3d372713, v0
	v_mul_f32_e32 v5, v0, v5
	v_fma_f32 v1, v1, v8, v13
	v_fma_f32 v5, v0, v5, v0
	v_mul_f32_e32 v7, 0x3d372713, v1
	v_mul_f32_e32 v5, 0x3fcc422a, v5
	v_mul_f32_e32 v7, v1, v7
	v_mul_f32_e32 v5, 0xbfb8aa3b, v5
	v_fma_f32 v7, v1, v7, v1
	v_exp_f32_e32 v5, v5
	v_mul_f32_e32 v7, 0x3fcc422a, v7
	v_mul_f32_e32 v7, 0xbfb8aa3b, v7
	v_exp_f32_e32 v7, v7
	v_add_f32_e32 v5, 1.0, v5
	v_rcp_f32_e32 v5, v5
	v_fmac_f32_e32 v15, v3, v4
	v_add_f32_e32 v7, 1.0, v7
	v_rcp_f32_e32 v7, v7
	v_mul_f32_e32 v0, v0, v5
	v_cvt_pk_bf16_f32 v0, v0, s0
	ds_write_b16 v122, v0 offset:8448
	v_mul_f32_e32 v0, v1, v7
	v_fma_f32 v1, v2, v6, v14
	v_mul_f32_e32 v2, 0x3d372713, v1
	v_mul_f32_e32 v3, 0x3d372713, v15
	v_mul_f32_e32 v2, v1, v2
	v_mul_f32_e32 v3, v15, v3
	v_fma_f32 v2, v1, v2, v1
	v_fma_f32 v3, v15, v3, v15
	v_mul_f32_e32 v2, 0x3fcc422a, v2
	v_mul_f32_e32 v3, 0x3fcc422a, v3
	v_mul_f32_e32 v2, 0xbfb8aa3b, v2
	v_mul_f32_e32 v3, 0xbfb8aa3b, v3
	v_exp_f32_e32 v2, v2
	v_exp_f32_e32 v3, v3
	v_cvt_pk_bf16_f32 v0, v0, s0
	ds_write_b16 v122, v0 offset:8480
	v_add_f32_e32 v2, 1.0, v2
	v_add_f32_e32 v0, 1.0, v3
	v_rcp_f32_e32 v2, v2
	v_rcp_f32_e32 v0, v0
	v_lshl_add_u64 v[4:5], v[94:95], 0, s[68:69]
	v_lshlrev_b64 v[4:5], 12, v[4:5]
	v_mul_f32_e32 v1, v1, v2
	v_mul_f32_e32 v0, v15, v0
	v_cvt_pk_bf16_f32 v1, v1, s0
	v_cvt_pk_bf16_f32 v0, v0, s0
	ds_write_b16 v122, v1 offset:8512
	ds_write_b16 v122, v0 offset:8544
	s_waitcnt lgkmcnt(0)
	ds_read_b64 v[0:1], v123 offset:8448
	v_lshl_add_u64 v[2:3], v[92:93], 0, s[38:39]
	v_lshl_add_u64 v[2:3], v[2:3], 0, v[4:5]
	s_waitcnt lgkmcnt(0)
	global_store_dwordx2 v[2:3], v[0:1], off
	s_waitcnt lgkmcnt(0)
	s_cbranch_scc0 .LBB0_649
